# v26: v23 with the carry-chain pads widened (s_nop 1) in the pipelined mlstm_out loop
# speedup vs baseline: 1.0118x; 1.0118x over previous
.LBB0_844:
	s_or_b64 exec, exec, s[10:11]
	s_waitcnt vmcnt(0)
	v_mov_b32_e32 v18, v232
	s_waitcnt vmcnt(0) lgkmcnt(0)
	s_barrier
	s_nop 0
	v_ashrrev_i32_e32 v19, 6, v18
	v_cmp_gt_i32_e32 vcc, 64, v19
	s_and_saveexec_b64 s[10:11], vcc
	s_mov_b64 s[36:37], 0x4000
	s_mov_b64 s[40:41], 0x2200000
	s_cbranch_execz .LBB0_847
	s_load_dwordx2 s[14:15], s[44:45], 0x48
	v_readlane_b32 s26, v255, 32
	v_lshlrev_b32_e32 v1, 6, v18
	v_readlane_b32 s27, v255, 33
	v_and_b32_e32 v1, 0xfc0, v1
	s_waitcnt lgkmcnt(0)
	s_add_u32 s14, s14, s26
	s_addc_u32 s15, s15, s27
	global_load_dwordx4 v[2:5], v1, s[14:15]
	global_load_dwordx4 v[6:9], v1, s[14:15] offset:16
	global_load_dwordx4 v[10:13], v1, s[14:15] offset:32
	global_load_dwordx4 v[14:17], v1, s[14:15] offset:48
	v_readlane_b32 s6, v255, 30
	s_sub_i32 s6, s62, s6
	s_lshr_b32 s14, s6, 6
	s_lshl_b32 s6, s6, 6
	s_mul_i32 s15, s14, 0x1100
	s_and_b32 s6, s6, 0xfc0
	v_cmp_lt_i32_e32 vcc, v231, v225
	s_add_i32 s14, s15, s6
	s_and_b32 s6, s62, 63
	v_cndmask_b32_e32 v1, v223, v231, vcc
	v_cmp_lt_i32_e32 vcc, v230, v225
	s_lshl_b32 s6, s6, 6
	s_add_i32 s6, s6, s15
	v_cndmask_b32_e32 v20, v223, v230, vcc
	v_cmp_lt_i32_e32 vcc, v229, v225
	v_lshlrev_b32_e32 v26, 2, v20
	s_load_dwordx2 s[26:27], s[44:45], 0xb0
	v_cndmask_b32_e32 v20, v223, v229, vcc
	v_cmp_lt_i32_e32 vcc, v222, v225
	v_lshlrev_b32_e32 v27, 2, v20
	v_add_u32_e32 v19, s6, v19
	v_cndmask_b32_e32 v20, v223, v222, vcc
	v_lshlrev_b32_e32 v28, 2, v20
	v_add_u32_e32 v20, 0x100, v19
	v_ashrrev_i32_e32 v21, 31, v20
	v_lshlrev_b64 v[20:21], 11, v[20:21]
	v_and_b32_e32 v18, 63, v18
	v_lshl_or_b32 v20, v18, 5, v20
	v_add_u32_e32 v29, 0xf8, v19
	s_waitcnt lgkmcnt(0)
	v_lshl_add_u64 v[18:19], s[26:27], 0, v[20:21]
	s_mov_b64 s[26:27], 0x25610000
	v_lshlrev_b32_e32 v1, 2, v1
	s_addk_i32 s14, 0x138
	v_lshl_add_u64 v[18:19], v[18:19], 0, s[26:27]
	s_mov_b64 s[26:27], 0
	v_lshl_add_u64 v[62:63], v[18:19], 0, s[40:41]
	global_load_dwordx4 v[100:103], v[18:19], off offset:16
	global_load_dwordx4 v[104:107], v[18:19], off
	global_load_dwordx4 v[108:111], v[62:63], off
	global_load_dwordx4 v[112:115], v[62:63], off offset:16
	v_add_co_u32_e32 v64, vcc, s92, v18
	s_nop 1
	v_addc_co_u32_e32 v65, vcc, -1, v19, vcc
	global_load_dwordx4 v[116:119], v[64:65], off
	v_add_co_u32_e32 v64, vcc, s93, v18
	s_nop 1
	v_addc_co_u32_e32 v65, vcc, -1, v19, vcc
	global_load_dwordx4 v[120:123], v[64:65], off
	v_add_co_u32_e32 v64, vcc, s94, v18
	s_nop 1
	v_addc_co_u32_e32 v65, vcc, -1, v19, vcc
	global_load_dwordx4 v[124:127], v[64:65], off offset:-4080
	v_add_co_u32_e32 v64, vcc, s95, v18
	s_nop 1
	v_addc_co_u32_e32 v65, vcc, -1, v19, vcc
	global_load_dwordx4 v[128:131], v[64:65], off offset:-4080
	s_waitcnt vmcnt(0)
.LBB0_846:
	s_waitcnt vmcnt(2)
	v_mov_b32_e32 v20, v100
	v_mov_b32_e32 v21, v101
	v_mov_b32_e32 v22, v102
	v_mov_b32_e32 v23, v103
	v_mov_b32_e32 v30, v104
	v_mov_b32_e32 v31, v105
	v_mov_b32_e32 v32, v106
	v_mov_b32_e32 v33, v107
	v_mov_b32_e32 v34, v108
	v_mov_b32_e32 v35, v109
	v_mov_b32_e32 v36, v110
	v_mov_b32_e32 v37, v111
	v_mov_b32_e32 v38, v112
	v_mov_b32_e32 v39, v113
	v_mov_b32_e32 v40, v114
	v_mov_b32_e32 v41, v115
	v_mov_b32_e32 v132, v116
	v_mov_b32_e32 v133, v117
	v_mov_b32_e32 v134, v118
	v_mov_b32_e32 v135, v119
	v_mov_b32_e32 v136, v120
	v_mov_b32_e32 v137, v121
	v_mov_b32_e32 v138, v122
	v_mov_b32_e32 v139, v123
	v_mov_b32_e32 v140, v124
	v_mov_b32_e32 v141, v125
	v_mov_b32_e32 v142, v126
	v_mov_b32_e32 v143, v127
	v_mov_b32_e32 v144, v128
	v_mov_b32_e32 v145, v129
	v_mov_b32_e32 v146, v130
	v_mov_b32_e32 v147, v131
	v_lshl_add_u64 v[60:61], v[18:19], 0, s[36:37]
	v_lshl_add_u64 v[62:63], v[60:61], 0, s[40:41]
	global_load_dwordx4 v[100:103], v[60:61], off offset:16
	global_load_dwordx4 v[104:107], v[60:61], off
	global_load_dwordx4 v[108:111], v[62:63], off
	global_load_dwordx4 v[112:115], v[62:63], off offset:16
	v_add_co_u32_e32 v64, vcc, s92, v60
	s_nop 1
	v_addc_co_u32_e32 v65, vcc, -1, v61, vcc
	global_load_dwordx4 v[116:119], v[64:65], off
	v_add_co_u32_e32 v64, vcc, s93, v60
	s_nop 1
	v_addc_co_u32_e32 v65, vcc, -1, v61, vcc
	global_load_dwordx4 v[120:123], v[64:65], off
	v_add_co_u32_e32 v64, vcc, s94, v60
	s_nop 1
	v_addc_co_u32_e32 v65, vcc, -1, v61, vcc
	global_load_dwordx4 v[124:127], v[64:65], off offset:-4080
	v_add_co_u32_e32 v64, vcc, s95, v60
	s_nop 1
	v_addc_co_u32_e32 v65, vcc, -1, v61, vcc
	global_load_dwordx4 v[128:131], v[64:65], off offset:-4080
	v_add_u32_e32 v29, 8, v29
	v_lshlrev_b32_e32 v25, 16, v30
	v_lshlrev_b32_e32 v24, 16, v34
	v_add_f32_e32 v44, v24, v25
	v_and_b32_e32 v24, 0xffff0000, v34
	v_and_b32_e32 v25, 0xffff0000, v30
	v_add_f32_e32 v45, v24, v25
	v_lshlrev_b32_e32 v24, 16, v35
	v_lshlrev_b32_e32 v25, 16, v31
	v_add_f32_e32 v46, v24, v25
	v_and_b32_e32 v24, 0xffff0000, v35
	v_and_b32_e32 v25, 0xffff0000, v31
	v_add_f32_e32 v47, v24, v25
	v_lshlrev_b32_e32 v24, 16, v36
	v_lshlrev_b32_e32 v25, 16, v32
	v_add_f32_e32 v48, v24, v25
	v_and_b32_e32 v24, 0xffff0000, v36
	v_and_b32_e32 v25, 0xffff0000, v32
	v_add_f32_e32 v49, v24, v25
	v_lshlrev_b32_e32 v24, 16, v37
	v_lshlrev_b32_e32 v25, 16, v33
	v_add_f32_e32 v50, v24, v25
	v_and_b32_e32 v24, 0xffff0000, v37
	v_and_b32_e32 v25, 0xffff0000, v33
	v_add_f32_e32 v51, v24, v25
	v_lshlrev_b32_e32 v24, 16, v20
	v_lshlrev_b32_e32 v25, 16, v38
	v_add_f32_e32 v31, v25, v24
	v_and_b32_e32 v24, 0xffff0000, v38
	v_and_b32_e32 v20, 0xffff0000, v20
	v_add_f32_e32 v30, v24, v20
	v_lshlrev_b32_e32 v25, 16, v21
	v_lshlrev_b32_e32 v33, 16, v39
	v_and_b32_e32 v32, 0xffff0000, v39
	v_and_b32_e32 v24, 0xffff0000, v21
	v_lshlrev_b32_e32 v21, 16, v22
	v_lshlrev_b32_e32 v35, 16, v40
	v_and_b32_e32 v34, 0xffff0000, v40
	v_and_b32_e32 v20, 0xffff0000, v22
	v_lshlrev_b32_e32 v37, 16, v23
	v_lshlrev_b32_e32 v39, 16, v41
	v_and_b32_e32 v38, 0xffff0000, v41
	v_and_b32_e32 v36, 0xffff0000, v23
	v_pk_add_f32 v[22:23], v[20:21], v[34:35]
	v_pk_add_f32 v[20:21], v[36:37], v[38:39]
	v_mul_f32_e32 v38, v44, v44
	v_fmac_f32_e32 v38, v45, v45
	v_fmac_f32_e32 v38, v46, v46
	v_fmac_f32_e32 v38, v47, v47
	v_fmac_f32_e32 v38, v48, v48
	v_fmac_f32_e32 v38, v49, v49
	v_fmac_f32_e32 v38, v50, v50
	v_fmac_f32_e32 v38, v51, v51
	v_pk_add_f32 v[24:25], v[24:25], v[32:33]
	v_fmac_f32_e32 v38, v31, v31
	v_pk_mul_f32 v[32:33], v[24:25], v[24:25]
	v_fmac_f32_e32 v38, v30, v30
	v_add_f32_e32 v33, v33, v38
	v_pk_mul_f32 v[34:35], v[22:23], v[22:23]
	v_add_f32_e32 v32, v32, v33
	v_add_f32_e32 v32, v35, v32
	v_pk_mul_f32 v[36:37], v[20:21], v[20:21]
	v_add_f32_e32 v32, v34, v32
	v_add_f32_e32 v32, v37, v32
	v_add_f32_e32 v32, v36, v32
	ds_bpermute_b32 v33, v1, v32
	s_waitcnt lgkmcnt(0)
	v_add_f32_e32 v32, v32, v33
	ds_bpermute_b32 v33, v26, v32
	s_waitcnt lgkmcnt(0)
	v_add_f32_e32 v32, v32, v33
	ds_bpermute_b32 v33, v27, v32
	s_waitcnt lgkmcnt(0)
	v_add_f32_e32 v32, v32, v33
	ds_bpermute_b32 v33, v28, v32
	s_waitcnt lgkmcnt(0)
	v_add_f32_e32 v32, v32, v33
	v_fmamk_f32 v32, v32, 0x3b800000, v234
	v_cmp_gt_f32_e32 vcc, s90, v32
	v_mul_f32_e32 v33, 0x4b800000, v32
	s_nop 0
	v_cndmask_b32_e32 v32, v32, v33, vcc
	v_rsq_f32_e32 v32, v32
	s_nop 0
	v_mul_f32_e32 v33, 0x45800000, v32
	v_cndmask_b32_e32 v32, v32, v33, vcc
	v_add_co_u32_e32 v42, vcc, s92, v18
	v_mul_f32_e32 v33, v44, v32
	s_nop 0
	v_addc_co_u32_e32 v43, vcc, -1, v19, vcc
	v_add_co_u32_e32 v38, vcc, s93, v18
	v_mov_b32_e32 v34, v132
	v_mov_b32_e32 v35, v133
	v_mov_b32_e32 v36, v134
	v_mov_b32_e32 v37, v135
	s_nop 0
	v_addc_co_u32_e32 v39, vcc, -1, v19, vcc
	v_mov_b32_e32 v38, v136
	v_mov_b32_e32 v39, v137
	v_mov_b32_e32 v40, v138
	v_mov_b32_e32 v41, v139
	v_mul_f32_e32 v33, v2, v33
	v_mul_f32_e32 v31, v31, v32
	v_mul_f32_e32 v31, v10, v31
	v_mul_f32_e32 v30, v30, v32
	v_mul_f32_e32 v30, v11, v30
	v_mul_f32_e32 v25, v25, v32
	v_mul_f32_e32 v25, v12, v25
	v_mul_f32_e32 v24, v24, v32
	v_mul_f32_e32 v24, v13, v24
	v_mul_f32_e32 v23, v23, v32
	v_mul_f32_e32 v23, v14, v23
	v_mul_f32_e32 v22, v22, v32
	v_mul_f32_e32 v22, v15, v22
	v_mul_f32_e32 v21, v21, v32
	v_mul_f32_e32 v21, v16, v21
	v_mul_f32_e32 v20, v20, v32
	v_mul_f32_e32 v20, v17, v20
	v_lshlrev_b32_e32 v44, 16, v34
	v_mul_f32_e32 v33, v33, v44
	v_and_b32_e32 v34, 0xffff0000, v34
	v_lshlrev_b32_e32 v44, 16, v38
	v_mul_f32_e32 v33, v33, v44
	v_mul_f32_e32 v44, v45, v32
	v_mul_f32_e32 v44, v3, v44
	v_mul_f32_e32 v34, v44, v34
	v_and_b32_e32 v38, 0xffff0000, v38
	v_mul_f32_e32 v34, v34, v38
	s_nop 1
	v_cvt_pk_bf16_f32 v34, v33, v34
	v_mul_f32_e32 v33, v46, v32
	v_mul_f32_e32 v33, v4, v33
	v_lshlrev_b32_e32 v38, 16, v35
	v_mul_f32_e32 v33, v33, v38
	v_lshlrev_b32_e32 v38, 16, v39
	v_mul_f32_e32 v33, v33, v38
	v_mul_f32_e32 v38, v47, v32
	v_mul_f32_e32 v38, v5, v38
	v_and_b32_e32 v35, 0xffff0000, v35
	v_mul_f32_e32 v35, v38, v35
	v_and_b32_e32 v38, 0xffff0000, v39
	v_mul_f32_e32 v35, v35, v38
	s_nop 1
	v_cvt_pk_bf16_f32 v35, v33, v35
	v_mul_f32_e32 v33, v48, v32
	v_mul_f32_e32 v33, v6, v33
	v_lshlrev_b32_e32 v38, 16, v36
	v_mul_f32_e32 v33, v33, v38
	v_lshlrev_b32_e32 v38, 16, v40
	v_mul_f32_e32 v33, v33, v38
	v_mul_f32_e32 v38, v49, v32
	v_mul_f32_e32 v38, v7, v38
	v_and_b32_e32 v36, 0xffff0000, v36
	v_mul_f32_e32 v36, v38, v36
	v_and_b32_e32 v38, 0xffff0000, v40
	v_mul_f32_e32 v36, v36, v38
	s_nop 1
	v_cvt_pk_bf16_f32 v36, v33, v36
	v_mul_f32_e32 v33, v50, v32
	v_mul_f32_e32 v33, v8, v33
	v_lshlrev_b32_e32 v38, 16, v37
	v_mul_f32_e32 v33, v33, v38
	v_lshlrev_b32_e32 v38, 16, v41
	v_mul_f32_e32 v33, v33, v38
	v_mul_f32_e32 v38, v51, v32
	v_mul_f32_e32 v38, v9, v38
	v_and_b32_e32 v37, 0xffff0000, v37
	v_mul_f32_e32 v37, v38, v37
	v_and_b32_e32 v38, 0xffff0000, v41
	v_mul_f32_e32 v37, v37, v38
	s_nop 1
	v_cvt_pk_bf16_f32 v37, v33, v37
	global_store_dwordx4 v[42:43], v[34:37], off
	v_add_co_u32_e32 v42, vcc, s94, v18
	s_nop 1
	v_addc_co_u32_e32 v43, vcc, -1, v19, vcc
	v_add_co_u32_e32 v38, vcc, s95, v18
	v_mov_b32_e32 v34, v140
	v_mov_b32_e32 v35, v141
	v_mov_b32_e32 v36, v142
	v_mov_b32_e32 v37, v143
	s_nop 0
	v_addc_co_u32_e32 v39, vcc, -1, v19, vcc
	v_mov_b32_e32 v38, v144
	v_mov_b32_e32 v39, v145
	v_mov_b32_e32 v40, v146
	v_mov_b32_e32 v41, v147
	v_cmp_le_i32_e32 vcc, s14, v29
	v_lshl_add_u64 v[18:19], v[18:19], 0, s[36:37]
	s_or_b64 s[26:27], vcc, s[26:27]
	v_lshlrev_b32_e32 v33, 16, v34
	v_mul_f32_e32 v31, v31, v33
	v_lshlrev_b32_e32 v33, 16, v38
	v_mul_f32_e32 v31, v31, v33
	v_and_b32_e32 v33, 0xffff0000, v34
	v_mul_f32_e32 v30, v30, v33
	v_and_b32_e32 v33, 0xffff0000, v38
	v_mul_f32_e32 v30, v30, v33
	s_nop 1
	v_cvt_pk_bf16_f32 v34, v31, v30
	v_lshlrev_b32_e32 v30, 16, v35
	v_mul_f32_e32 v25, v25, v30
	v_lshlrev_b32_e32 v30, 16, v39
	v_mul_f32_e32 v25, v25, v30
	v_and_b32_e32 v30, 0xffff0000, v35
	v_mul_f32_e32 v24, v24, v30
	v_and_b32_e32 v30, 0xffff0000, v39
	v_mul_f32_e32 v24, v24, v30
	s_nop 1
	v_cvt_pk_bf16_f32 v35, v25, v24
	v_lshlrev_b32_e32 v24, 16, v36
	v_mul_f32_e32 v23, v23, v24
	v_lshlrev_b32_e32 v24, 16, v40
	v_mul_f32_e32 v23, v23, v24
	v_and_b32_e32 v24, 0xffff0000, v36
	v_mul_f32_e32 v22, v22, v24
	v_and_b32_e32 v24, 0xffff0000, v40
	v_mul_f32_e32 v22, v22, v24
	s_nop 1
	v_cvt_pk_bf16_f32 v36, v23, v22
	v_lshlrev_b32_e32 v22, 16, v37
	v_mul_f32_e32 v21, v21, v22
	v_lshlrev_b32_e32 v22, 16, v41
	v_mul_f32_e32 v21, v21, v22
	v_and_b32_e32 v22, 0xffff0000, v37
	v_mul_f32_e32 v20, v20, v22
	v_and_b32_e32 v22, 0xffff0000, v41
	v_mul_f32_e32 v20, v20, v22
	s_nop 1
	v_cvt_pk_bf16_f32 v37, v21, v20
	global_store_dwordx4 v[42:43], v[34:37], off offset:-4080
	s_andn2_b64 exec, exec, s[26:27]
	s_cbranch_execnz .LBB0_846
